# v46 + attention exp-section packed sub/mul only
# speedup vs baseline: 1.0030x; 1.0030x over previous
; DEV f32x4 mfma32(bf16x8 a, bf16x8 b, f32x4 c) { return __builtin_amdgcn_mfma_f32_16x16x32_bf16(a, b, c, 0, 0, 0); }
; DEV void attn_prompt_group(const Params& p, int l, int item, unsigned char* smem) {
;     ...
; #pragma unroll
;     for (int i = 0; i < 4; ++i) {
;       const int c = tid + i * 512, r = c & 255, kc = c >> 8;
;       bf16_t* dst = Vt + (kc * 8) * 264 + r;
;       dst[0 * 264] = (bf16_t)(v[i].x & 0xffff); dst[1 * 264] = (bf16_t)(v[i].x >> 16);
;       dst[2 * 264] = (bf16_t)(v[i].y & 0xffff); dst[3 * 264] = (bf16_t)(v[i].y >> 16);
;       dst[4 * 264] = (bf16_t)(v[i].z & 0xffff); dst[5 * 264] = (bf16_t)(v[i].z >> 16);
;       dst[6 * 264] = (bf16_t)(v[i].w & 0xffff); dst[7 * 264] = (bf16_t)(v[i].w >> 16);
;     }
;   }
;   bf16x8 kf[9][2];
; #pragma unroll
;   for (int t = 0; t < 9; ++t) {
;     const int tok = nb * 128 - 128 + (w + t) * 16 + fr;
; #pragma unroll
;     for (int ks = 0; ks < 2; ++ks) {
;       u32x4 v = (u32x4){0u, 0u, 0u, 0u};
;       if (tok >= 0) v = *(const u32x4*)(Z + ((size_t)b * SEQ + tok) * NIN + AK + kvh * 64 + ks * 32 + fq * 8);
;       kf[t][ks] = __builtin_bit_cast(bf16x8, v);
;     }
;   }
;   __syncthreads();
;   const int qi0 = w * 16 + fr;
; #pragma unroll 1
;   for (int g = 0; g < 4; ++g) {
;     const int h = kvh * 4 + g;
;     int qi = qi0; asm volatile("" : "+v"(qi));
;     bf16x8 qf[2];
; #pragma unroll
;     for (int ks = 0; ks < 2; ++ks) qf[ks] = __builtin_bit_cast(bf16x8, *(const u32x4*)(Z + (rowbase + qi) * NIN + AQ + h * 64 + ks * 32 + fq * 8));
;     f32x4 s[9];
; #pragma unroll
;     for (int t = 0; t < 9; ++t) {
;       s[t] = (f32x4){0.f, 0.f, 0.f, 0.f};
; #pragma unroll
;       for (int ks = 0; ks < 2; ++ks) s[t] = mfma32(kf[t][ks], qf[ks], s[t]);
;     }
;     const float slope = exp2f(-(float)(h + 1));
;     const float sink = p.in[I_SINKS][l * 8 + h];
;     float mx = sink;
; #pragma unroll
;     for (int t = 0; t < 9; ++t)
; #pragma unroll
;       for (int j = 0; j < 4; ++j) {
;         const int si = (w + t) * 16 + fq * 4 + j;
;         const bool ok = (si > qi) && (si <= 128 + qi) && (nb > 0 || si >= 128);
;         const float sc = ok ? s[t][j] * 0.125f - slope * (float)(128 + qi - si) : -INFINITY;
;         s[t][j] = sc; mx = fmaxf(mx, sc);
.Lattn_vw1:
	ds_write_b16 v186, v218
	ds_write_b16_d16_hi v186, v218 offset:528
	ds_write_b16 v186, v219 offset:1056
	ds_write_b16_d16_hi v186, v219 offset:1584
	ds_write_b16 v186, v220 offset:2112
	ds_write_b16_d16_hi v186, v220 offset:2640
	ds_write_b16 v186, v221 offset:3168
	ds_write_b16_d16_hi v186, v221 offset:3696
	ds_write_b16 v188, v222
	ds_write_b16_d16_hi v188, v222 offset:528
	ds_write_b16 v188, v223 offset:1056
	ds_write_b16_d16_hi v188, v223 offset:1584
	ds_write_b16 v188, v224 offset:2112
	ds_write_b16_d16_hi v188, v224 offset:2640
	ds_write_b16 v188, v225 offset:3168
	ds_write_b16_d16_hi v188, v225 offset:3696
	ds_write_b16 v190, v226
	ds_write_b16_d16_hi v190, v226 offset:528
	ds_write_b16 v190, v227 offset:1056
	ds_write_b16_d16_hi v190, v227 offset:1584
	ds_write_b16 v190, v228 offset:2112
	ds_write_b16_d16_hi v190, v228 offset:2640
	ds_write_b16 v190, v229 offset:3168
	ds_write_b16_d16_hi v190, v229 offset:3696
	ds_write_b16 v192, v230
	ds_write_b16_d16_hi v192, v230 offset:528
	ds_write_b16 v192, v231 offset:1056
	ds_write_b16_d16_hi v192, v231 offset:1584
	ds_write_b16 v192, v232 offset:2112
	ds_write_b16_d16_hi v192, v232 offset:2640
	ds_write_b16 v192, v233 offset:3168
	ds_write_b16_d16_hi v192, v233 offset:3696
	v_cndmask_b32_e64 v72, 0, 1, s[34:35]
	v_readlane_b32 s2, v248, 46
	v_readfirstlane_b32 s1, v72
	s_lshl_b32 s1, s1, 2
	s_add_i32 s2, s2, s1
	s_ashr_i32 s3, s2, 31
	s_lshl_b64 s[2:3], s[2:3], 2
	s_add_u32 s18, s82, s2
	s_addc_u32 s19, s83, s3
	s_or_b32 s6, s1, 1
	v_lshlrev_b32_e32 v107, 2, v78
	s_cmp_lg_u32 s8, 0
	v_or_b32_e32 v108, v107, v75
	s_movk_i32 s1, 0x7f
	s_cselect_b64 s[88:89], -1, 0
	v_cmp_lt_i32_e32 vcc, s1, v108
	s_movk_i32 s84, 0x7e
	s_or_b64 s[36:37], s[88:89], vcc
	v_cmp_lt_i32_e32 vcc, s84, v108
	v_or_b32_e32 v110, 2, v108
	s_or_b64 s[38:39], s[88:89], vcc
	v_cmp_lt_i32_e32 vcc, s1, v110
	v_or_b32_e32 v111, 3, v108
	s_or_b64 s[40:41], s[88:89], vcc
	v_cmp_lt_i32_e32 vcc, s1, v111
	v_or_b32_e32 v112, v81, v107
	s_or_b64 s[60:61], s[88:89], vcc
	v_cmp_lt_i32_e32 vcc, s1, v112
	s_or_b64 s[62:63], s[88:89], vcc
	v_cmp_lt_i32_e32 vcc, s84, v112
	v_or_b32_e32 v114, 2, v112
	s_or_b64 s[64:65], s[88:89], vcc
	v_cmp_lt_i32_e32 vcc, s1, v114
	v_or_b32_e32 v115, 3, v112
	s_or_b64 s[66:67], s[88:89], vcc
	v_cmp_lt_i32_e32 vcc, s1, v115
	v_or_b32_e32 v116, v83, v107
	s_or_b64 s[68:69], s[88:89], vcc
	v_cmp_lt_i32_e32 vcc, s1, v116
	s_or_b64 s[70:71], s[88:89], vcc
	v_cmp_lt_i32_e32 vcc, s84, v116
	v_or_b32_e32 v118, 2, v116
	s_or_b64 s[72:73], s[88:89], vcc
	v_cmp_lt_i32_e32 vcc, s1, v118
	v_or_b32_e32 v119, 3, v116
	v_add_u32_e32 v98, 0, v84
	v_mul_lo_u32 v84, v77, s75
	s_or_b64 s[74:75], s[88:89], vcc
	v_cmp_lt_i32_e32 vcc, s1, v119
	v_or_b32_e32 v120, v86, v107
	s_or_b64 s[96:97], s[88:89], vcc
	v_cmp_lt_i32_e32 vcc, s1, v120
	s_or_b64 s[4:5], s[88:89], vcc
	v_cmp_lt_i32_e32 vcc, s84, v120
	v_or_b32_e32 v122, 2, v120
	s_or_b64 s[26:27], s[88:89], vcc
	v_cmp_lt_i32_e32 vcc, s1, v122
	v_or_b32_e32 v123, 3, v120
	s_or_b64 s[20:21], s[88:89], vcc
	v_cmp_lt_i32_e32 vcc, s1, v123
	v_or_b32_e32 v124, v88, v107
	s_or_b64 s[44:45], s[88:89], vcc
	v_cmp_lt_i32_e32 vcc, s1, v124
	s_or_b64 s[46:47], s[88:89], vcc
	v_cmp_lt_i32_e32 vcc, s84, v124
	v_or_b32_e32 v126, 2, v124
	s_or_b64 s[48:49], s[88:89], vcc
	v_cmp_lt_i32_e32 vcc, s1, v126
	v_or_b32_e32 v127, 3, v124
	s_or_b64 s[50:51], s[88:89], vcc
	v_cmp_lt_i32_e32 vcc, s1, v127
	v_or_b32_e32 v128, v89, v107
	s_or_b64 s[52:53], s[88:89], vcc
	v_cmp_lt_i32_e32 vcc, s1, v128
	s_or_b64 s[54:55], s[88:89], vcc
	v_cmp_lt_i32_e32 vcc, s84, v128
	v_or_b32_e32 v130, 2, v128
	s_or_b64 s[56:57], s[88:89], vcc
	v_cmp_lt_i32_e32 vcc, s1, v130
	v_or_b32_e32 v131, 3, v128
	s_or_b64 s[58:59], s[88:89], vcc
	v_cmp_lt_i32_e32 vcc, s1, v131
	v_or_b32_e32 v132, v93, v107
	s_or_b64 s[42:43], s[88:89], vcc
	v_cmp_lt_i32_e32 vcc, s1, v132
	s_or_b64 s[2:3], s[88:89], vcc
	v_cmp_lt_i32_e32 vcc, s84, v132
	v_or_b32_e32 v134, 2, v132
	s_mul_i32 s92, s8, 0x1b0000
	s_or_b64 s[8:9], s[88:89], vcc
	v_cmp_lt_i32_e32 vcc, s1, v134
	v_or_b32_e32 v135, 3, v132
	s_or_b64 s[12:13], s[88:89], vcc
	v_cmp_lt_i32_e32 vcc, s1, v135
	v_or_b32_e32 v136, v95, v107
	s_or_b64 s[14:15], s[88:89], vcc
	v_cmp_lt_i32_e32 vcc, s1, v136
	s_or_b64 s[16:17], s[88:89], vcc
	v_cmp_lt_i32_e32 vcc, s84, v136
	v_or_b32_e32 v138, 2, v136
	s_or_b64 s[76:77], s[88:89], vcc
	v_cmp_lt_i32_e32 vcc, s1, v138
	v_or_b32_e32 v139, 3, v136
	s_or_b64 s[78:79], s[88:89], vcc
	v_cmp_lt_i32_e32 vcc, s1, v139
	v_or_b32_e32 v140, v97, v107
	s_or_b64 s[80:81], s[88:89], vcc
	v_cmp_lt_i32_e32 vcc, s1, v140
	s_or_b64 s[82:83], s[88:89], vcc
	v_cmp_lt_i32_e32 vcc, s84, v140
	v_or_b32_e32 v142, 2, v140
	s_or_b64 s[84:85], s[88:89], vcc
	v_cmp_lt_i32_e32 vcc, s1, v142
	v_or_b32_e32 v143, 3, v140
	v_lshlrev_b32_e32 v99, 4, v74
	s_or_b64 s[86:87], s[88:89], vcc
	v_cmp_lt_i32_e32 vcc, s1, v143
	v_and_b32_e32 v92, 63, v74
	v_add_u32_e32 v91, 0, v84
	v_and_b32_e32 v99, 0x70, v99
	s_or_b64 s[88:89], s[88:89], vcc
	s_mul_i32 s91, s0, 0x3600000
	v_lshl_add_u32 v84, v76, 1, v91
	v_add_u32_e32 v91, v91, v99
	v_lshrrev_b32_e32 v99, 3, v92
	s_mul_hi_i32 s90, s0, 0x3600000
	s_add_u32 s0, s91, s92
	v_or_b32_e32 v106, v75, v76
	v_bitop3_b32 v113, v81, v107, v81 bitop3:3
	v_mul_u32_u24_e32 v81, 0x210, v76
	v_or_b32_e32 v76, 8, v99
	s_addc_u32 s1, s90, 0
	v_bitop3_b32 v117, v83, v107, v83 bitop3:3
	v_bitop3_b32 v133, v93, v107, v93 bitop3:3
	v_lshl_add_u32 v83, v77, 5, v98
	v_mul_u32_u24_e32 v93, 0x90, v76
	v_mov_b64_e32 v[76:77], s[0:1]
	v_mad_u64_u32 v[76:77], s[0:1], v99, s95, v[76:77]
	v_lshlrev_b32_e32 v72, 9, v72
	v_mov_b32_e32 v73, v169
; DEV f32x4 mfma32(bf16x8 a, bf16x8 b, f32x4 c) { return __builtin_amdgcn_mfma_f32_16x16x32_bf16(a, b, c, 0, 0, 0); }
; DEV void attn_prompt_group(const Params& p, int l, int item, unsigned char* smem) {
;     ...
;     for (int ks = 0; ks < 2; ++ks) qf[ks] = __builtin_bit_cast(bf16x8, *(const u32x4*)(Z + (rowbase + qi) * NIN + AQ + h * 64 + ks * 32 + fq * 8));
;     f32x4 s[9];
; #pragma unroll
;     for (int t = 0; t < 9; ++t) {
;       s[t] = (f32x4){0.f, 0.f, 0.f, 0.f};
; #pragma unroll
;       for (int ks = 0; ks < 2; ++ks) s[t] = mfma32(kf[t][ks], qf[ks], s[t]);
;     }
;     const float slope = exp2f(-(float)(h + 1));
;     const float sink = p.in[I_SINKS][l * 8 + h];
;     float mx = sink;
; #pragma unroll
;     for (int t = 0; t < 9; ++t)
; #pragma unroll
;       for (int j = 0; j < 4; ++j) {
;         const int si = (w + t) * 16 + fq * 4 + j;
;         const bool ok = (si > qi) && (si <= 128 + qi) && (nb > 0 || si >= 128);
;         const float sc = ok ? s[t][j] * 0.125f - slope * (float)(128 + qi - si) : -INFINITY;
;         s[t][j] = sc; mx = fmaxf(mx, sc);
	v_mad_i64_i32 v[76:77], s[0:1], v75, s95, v[76:77]
	v_lshl_add_u64 v[76:77], v[76:77], 0, v[72:73]
	v_and_b32_e32 v73, 7, v74
	v_or_b32_e32 v144, 1, v107
	v_lshl_or_b32 v76, v73, 4, v76
	v_or_b32_e32 v72, s91, v72
	v_mov_b32_e32 v73, s90
	v_mul_u32_u24_e32 v92, 0x90, v99
	v_bitop3_b32 v121, v86, v107, v86 bitop3:3
	v_bitop3_b32 v125, v88, v107, v88 bitop3:3
	v_bitop3_b32 v129, v89, v107, v89 bitop3:3
	v_lshl_add_u32 v79, v79, 5, v98
	v_lshl_add_u32 v80, v80, 5, v98
	v_lshl_add_u32 v82, v82, 5, v98
	v_lshl_add_u32 v85, v85, 5, v98
	v_lshl_add_u32 v86, v87, 5, v98
	v_lshl_add_u32 v87, v90, 5, v98
	v_lshl_add_u32 v88, v94, 5, v98
	v_lshl_add_u32 v89, v96, 5, v98
	v_mul_u32_u24_e32 v78, 0x240, v78
	v_mul_u32_u24_e32 v90, 0x90, v144
	v_lshl_add_u64 v[72:73], s[28:29], 0, v[72:73]
	v_bitop3_b32 v109, v107, v75, v107 bitop3:3
	v_bitop3_b32 v137, v95, v107, v95 bitop3:3
	v_bitop3_b32 v141, v97, v107, v97 bitop3:3
	v_or_b32_e32 v145, 2, v107
	v_or_b32_e32 v146, 3, v107
	v_lshl_add_u64 v[100:101], s[28:29], 0, v[76:77]
	v_lshl_add_u64 v[102:103], v[72:73], 0, v[168:169]
	s_mov_b64 s[90:91], 0
	v_add_u32_e32 v147, v83, v81
	v_add_u32_e32 v148, v79, v81
	v_add_u32_e32 v149, v80, v81
	v_add_u32_e32 v150, v82, v81
	v_add_u32_e32 v151, v85, v81
	v_add_u32_e32 v152, v86, v81
	v_add_u32_e32 v153, v87, v81
	v_add_u32_e32 v154, v88, v81
	v_add_u32_e32 v155, v89, v81
	v_add_u32_e32 v156, v84, v78
	v_add_u32_e32 v157, v84, v90
	v_add_u32_e32 v158, v91, v92
	v_add_u32_e32 v159, v91, v93
	s_mov_b32 s94, 0x42fc0000
	s_mov_b32 s0, s92
	s_mov_b32 s1, 0
	v_mov_b64_e32 v[72:73], s[0:1]
	v_mad_i64_i32 v[72:73], s[0:1], v106, s95, v[72:73]
	v_lshl_add_u64 v[72:73], v[102:103], 0, v[72:73]
	v_add_co_u32_e32 v76, vcc, 0x4700000, v72
	s_nop 1
	v_addc_co_u32_e32 v77, vcc, 0, v73, vcc
	global_load_dwordx4 v[234:237], v[76:77], off offset:3072
	global_load_dwordx4 v[238:241], v[76:77], off offset:3136
	global_load_dword v242, v169, s[18:19]
	s_cmp_lg_u32 s92, 0
	s_cselect_b32 s0, -1, 0x7f
	v_add_u32_e32 v184, 0x80, v106
	v_mov_b32_e32 v185, 0x7f800000
	v_sub_u32_e32 v104, v184, v108
	v_add_u32_e32 v105, -3, v104
	v_add_u32_e32 v177, 3, v108
	v_cmp_gt_u32_e32 vcc, 0x80, v105
	v_cmp_lt_i32_e64 s[2:3], s0, v177
	v_cvt_f32_i32_e32 v179, v105
	s_and_b64 vcc, vcc, s[2:3]
	s_nop 1
	v_cndmask_b32_e32 v111, v185, v179, vcc
	v_add_u32_e32 v105, -2, v104
	v_add_u32_e32 v177, 2, v108
	v_cmp_gt_u32_e32 vcc, 0x80, v105
	v_cmp_lt_i32_e64 s[2:3], s0, v177
	v_cvt_f32_i32_e32 v179, v105
	s_and_b64 vcc, vcc, s[2:3]
	s_nop 1
	v_cndmask_b32_e32 v110, v185, v179, vcc
	v_add_u32_e32 v105, -1, v104
	v_add_u32_e32 v177, 1, v108
	v_cmp_gt_u32_e32 vcc, 0x80, v105
	v_cmp_lt_i32_e64 s[2:3], s0, v177
	v_cvt_f32_i32_e32 v179, v105
	s_and_b64 vcc, vcc, s[2:3]
	s_nop 1
	v_cndmask_b32_e32 v109, v185, v179, vcc
	v_cmp_gt_u32_e32 vcc, 0x80, v104
	v_cmp_lt_i32_e64 s[2:3], s0, v108
	v_cvt_f32_i32_e32 v179, v104
	s_and_b64 vcc, vcc, s[2:3]
	s_nop 1
	v_cndmask_b32_e32 v108, v185, v179, vcc
	v_sub_u32_e32 v104, v184, v112
	v_add_u32_e32 v105, -3, v104
	v_add_u32_e32 v177, 3, v112
	v_cmp_gt_u32_e32 vcc, 0x80, v105
	v_cmp_lt_i32_e64 s[2:3], s0, v177
	v_cvt_f32_i32_e32 v179, v105
	s_and_b64 vcc, vcc, s[2:3]
	s_nop 1
	v_cndmask_b32_e32 v115, v185, v179, vcc
	v_add_u32_e32 v105, -2, v104
	v_add_u32_e32 v177, 2, v112
	v_cmp_gt_u32_e32 vcc, 0x80, v105
	v_cmp_lt_i32_e64 s[2:3], s0, v177
	v_cvt_f32_i32_e32 v179, v105
	s_and_b64 vcc, vcc, s[2:3]
	s_nop 1
	v_cndmask_b32_e32 v114, v185, v179, vcc
	v_add_u32_e32 v105, -1, v104
	v_add_u32_e32 v177, 1, v112
	v_cmp_gt_u32_e32 vcc, 0x80, v105
	v_cmp_lt_i32_e64 s[2:3], s0, v177
	v_cvt_f32_i32_e32 v179, v105
	s_and_b64 vcc, vcc, s[2:3]
	s_nop 1
	v_cndmask_b32_e32 v113, v185, v179, vcc
	v_cmp_gt_u32_e32 vcc, 0x80, v104
	v_cmp_lt_i32_e64 s[2:3], s0, v112
	v_cvt_f32_i32_e32 v179, v104
	s_and_b64 vcc, vcc, s[2:3]
	s_nop 1
	v_cndmask_b32_e32 v112, v185, v179, vcc
	v_sub_u32_e32 v104, v184, v116
	v_add_u32_e32 v105, -3, v104
	v_add_u32_e32 v177, 3, v116
	v_cmp_gt_u32_e32 vcc, 0x80, v105
	v_cmp_lt_i32_e64 s[2:3], s0, v177
	v_cvt_f32_i32_e32 v179, v105
	s_and_b64 vcc, vcc, s[2:3]
	s_nop 1
	v_cndmask_b32_e32 v119, v185, v179, vcc
	v_add_u32_e32 v105, -2, v104
	v_add_u32_e32 v177, 2, v116
	v_cmp_gt_u32_e32 vcc, 0x80, v105
	v_cmp_lt_i32_e64 s[2:3], s0, v177
	v_cvt_f32_i32_e32 v179, v105
	s_and_b64 vcc, vcc, s[2:3]
	s_nop 1
	v_cndmask_b32_e32 v118, v185, v179, vcc
	v_add_u32_e32 v105, -1, v104
	v_add_u32_e32 v177, 1, v116
	v_cmp_gt_u32_e32 vcc, 0x80, v105
	v_cmp_lt_i32_e64 s[2:3], s0, v177
	v_cvt_f32_i32_e32 v179, v105
	s_and_b64 vcc, vcc, s[2:3]
	s_nop 1
	v_cndmask_b32_e32 v117, v185, v179, vcc
	v_cmp_gt_u32_e32 vcc, 0x80, v104
	v_cmp_lt_i32_e64 s[2:3], s0, v116
	v_cvt_f32_i32_e32 v179, v104
	s_and_b64 vcc, vcc, s[2:3]
	s_nop 1
	v_cndmask_b32_e32 v116, v185, v179, vcc
	v_sub_u32_e32 v104, v184, v120
	v_add_u32_e32 v105, -3, v104
	v_add_u32_e32 v177, 3, v120
	v_cmp_gt_u32_e32 vcc, 0x80, v105
	v_cmp_lt_i32_e64 s[2:3], s0, v177
	v_cvt_f32_i32_e32 v179, v105
	s_and_b64 vcc, vcc, s[2:3]
	s_nop 1
	v_cndmask_b32_e32 v123, v185, v179, vcc
	v_add_u32_e32 v105, -2, v104
	v_add_u32_e32 v177, 2, v120
	v_cmp_gt_u32_e32 vcc, 0x80, v105
	v_cmp_lt_i32_e64 s[2:3], s0, v177
	v_cvt_f32_i32_e32 v179, v105
; DEV void attn_prompt_group(const Params& p, int l, int item, unsigned char* smem) {
;     ...
; #pragma unroll
;     for (int t = 0; t < 9; ++t)
; #pragma unroll
;       for (int j = 0; j < 4; ++j) {
;         const int si = (w + t) * 16 + fq * 4 + j;
;         const bool ok = (si > qi) && (si <= 128 + qi) && (nb > 0 || si >= 128);
;         const float sc = ok ? s[t][j] * 0.125f - slope * (float)(128 + qi - si) : -INFINITY;
;         s[t][j] = sc; mx = fmaxf(mx, sc);
;       }
;     mx = fmaxf(mx, __shfl_xor(mx, 16)); mx = fmaxf(mx, __shfl_xor(mx, 32));
	s_and_b64 vcc, vcc, s[2:3]
	s_nop 1
	v_cndmask_b32_e32 v122, v185, v179, vcc
	v_add_u32_e32 v105, -1, v104
	v_add_u32_e32 v177, 1, v120
	v_cmp_gt_u32_e32 vcc, 0x80, v105
	v_cmp_lt_i32_e64 s[2:3], s0, v177
	v_cvt_f32_i32_e32 v179, v105
	s_and_b64 vcc, vcc, s[2:3]
	s_nop 1
	v_cndmask_b32_e32 v121, v185, v179, vcc
	v_cmp_gt_u32_e32 vcc, 0x80, v104
	v_cmp_lt_i32_e64 s[2:3], s0, v120
	v_cvt_f32_i32_e32 v179, v104
	s_and_b64 vcc, vcc, s[2:3]
	s_nop 1
	v_cndmask_b32_e32 v120, v185, v179, vcc
	v_sub_u32_e32 v104, v184, v124
	v_add_u32_e32 v105, -3, v104
	v_add_u32_e32 v177, 3, v124
	v_cmp_gt_u32_e32 vcc, 0x80, v105
	v_cmp_lt_i32_e64 s[2:3], s0, v177
	v_cvt_f32_i32_e32 v179, v105
	s_and_b64 vcc, vcc, s[2:3]
	s_nop 1
	v_cndmask_b32_e32 v127, v185, v179, vcc
	v_add_u32_e32 v105, -2, v104
	v_add_u32_e32 v177, 2, v124
	v_cmp_gt_u32_e32 vcc, 0x80, v105
	v_cmp_lt_i32_e64 s[2:3], s0, v177
	v_cvt_f32_i32_e32 v179, v105
	s_and_b64 vcc, vcc, s[2:3]
	s_nop 1
	v_cndmask_b32_e32 v126, v185, v179, vcc
	v_add_u32_e32 v105, -1, v104
	v_add_u32_e32 v177, 1, v124
	v_cmp_gt_u32_e32 vcc, 0x80, v105
	v_cmp_lt_i32_e64 s[2:3], s0, v177
	v_cvt_f32_i32_e32 v179, v105
	s_and_b64 vcc, vcc, s[2:3]
	s_nop 1
	v_cndmask_b32_e32 v125, v185, v179, vcc
	v_cmp_gt_u32_e32 vcc, 0x80, v104
	v_cmp_lt_i32_e64 s[2:3], s0, v124
	v_cvt_f32_i32_e32 v179, v104
	s_and_b64 vcc, vcc, s[2:3]
	s_nop 1
	v_cndmask_b32_e32 v124, v185, v179, vcc
	v_sub_u32_e32 v104, v184, v128
	v_add_u32_e32 v105, -3, v104
	v_add_u32_e32 v177, 3, v128
	v_cmp_gt_u32_e32 vcc, 0x80, v105
	v_cmp_lt_i32_e64 s[2:3], s0, v177
	v_cvt_f32_i32_e32 v179, v105
	s_and_b64 vcc, vcc, s[2:3]
	s_nop 1
	v_cndmask_b32_e32 v131, v185, v179, vcc
	v_add_u32_e32 v105, -2, v104
	v_add_u32_e32 v177, 2, v128
	v_cmp_gt_u32_e32 vcc, 0x80, v105
	v_cmp_lt_i32_e64 s[2:3], s0, v177
	v_cvt_f32_i32_e32 v179, v105
	s_and_b64 vcc, vcc, s[2:3]
	s_nop 1
	v_cndmask_b32_e32 v130, v185, v179, vcc
	v_add_u32_e32 v105, -1, v104
	v_add_u32_e32 v177, 1, v128
	v_cmp_gt_u32_e32 vcc, 0x80, v105
	v_cmp_lt_i32_e64 s[2:3], s0, v177
	v_cvt_f32_i32_e32 v179, v105
	s_and_b64 vcc, vcc, s[2:3]
	s_nop 1
	v_cndmask_b32_e32 v129, v185, v179, vcc
	v_cmp_gt_u32_e32 vcc, 0x80, v104
	v_cmp_lt_i32_e64 s[2:3], s0, v128
	v_cvt_f32_i32_e32 v179, v104
	s_and_b64 vcc, vcc, s[2:3]
	s_nop 1
	v_cndmask_b32_e32 v128, v185, v179, vcc
	v_sub_u32_e32 v104, v184, v132
	v_add_u32_e32 v105, -3, v104
	v_add_u32_e32 v177, 3, v132
	v_cmp_gt_u32_e32 vcc, 0x80, v105
	v_cmp_lt_i32_e64 s[2:3], s0, v177
	v_cvt_f32_i32_e32 v179, v105
	s_and_b64 vcc, vcc, s[2:3]
	s_nop 1
	v_cndmask_b32_e32 v135, v185, v179, vcc
	v_add_u32_e32 v105, -2, v104
	v_add_u32_e32 v177, 2, v132
	v_cmp_gt_u32_e32 vcc, 0x80, v105
	v_cmp_lt_i32_e64 s[2:3], s0, v177
	v_cvt_f32_i32_e32 v179, v105
	s_and_b64 vcc, vcc, s[2:3]
	s_nop 1
	v_cndmask_b32_e32 v134, v185, v179, vcc
	v_add_u32_e32 v105, -1, v104
	v_add_u32_e32 v177, 1, v132
	v_cmp_gt_u32_e32 vcc, 0x80, v105
	v_cmp_lt_i32_e64 s[2:3], s0, v177
	v_cvt_f32_i32_e32 v179, v105
	s_and_b64 vcc, vcc, s[2:3]
	s_nop 1
	v_cndmask_b32_e32 v133, v185, v179, vcc
	v_cmp_gt_u32_e32 vcc, 0x80, v104
	v_cmp_lt_i32_e64 s[2:3], s0, v132
	v_cvt_f32_i32_e32 v179, v104
	s_and_b64 vcc, vcc, s[2:3]
	s_nop 1
	v_cndmask_b32_e32 v132, v185, v179, vcc
	v_sub_u32_e32 v104, v184, v136
	v_add_u32_e32 v105, -3, v104
	v_add_u32_e32 v177, 3, v136
	v_cmp_gt_u32_e32 vcc, 0x80, v105
	v_cmp_lt_i32_e64 s[2:3], s0, v177
	v_cvt_f32_i32_e32 v179, v105
	s_and_b64 vcc, vcc, s[2:3]
	s_nop 1
	v_cndmask_b32_e32 v139, v185, v179, vcc
	v_add_u32_e32 v105, -2, v104
	v_add_u32_e32 v177, 2, v136
	v_cmp_gt_u32_e32 vcc, 0x80, v105
	v_cmp_lt_i32_e64 s[2:3], s0, v177
	v_cvt_f32_i32_e32 v179, v105
	s_and_b64 vcc, vcc, s[2:3]
	s_nop 1
	v_cndmask_b32_e32 v138, v185, v179, vcc
	v_add_u32_e32 v105, -1, v104
	v_add_u32_e32 v177, 1, v136
	v_cmp_gt_u32_e32 vcc, 0x80, v105
	v_cmp_lt_i32_e64 s[2:3], s0, v177
	v_cvt_f32_i32_e32 v179, v105
	s_and_b64 vcc, vcc, s[2:3]
	s_nop 1
	v_cndmask_b32_e32 v137, v185, v179, vcc
	v_cmp_gt_u32_e32 vcc, 0x80, v104
	v_cmp_lt_i32_e64 s[2:3], s0, v136
	v_cvt_f32_i32_e32 v179, v104
	s_and_b64 vcc, vcc, s[2:3]
	s_nop 1
	v_cndmask_b32_e32 v136, v185, v179, vcc
	v_sub_u32_e32 v104, v184, v140
	v_add_u32_e32 v105, -3, v104
	v_add_u32_e32 v177, 3, v140
	v_cmp_gt_u32_e32 vcc, 0x80, v105
	v_cmp_lt_i32_e64 s[2:3], s0, v177
	v_cvt_f32_i32_e32 v179, v105
	s_and_b64 vcc, vcc, s[2:3]
	s_nop 1
	v_cndmask_b32_e32 v143, v185, v179, vcc
	v_add_u32_e32 v105, -2, v104
	v_add_u32_e32 v177, 2, v140
	v_cmp_gt_u32_e32 vcc, 0x80, v105
	v_cmp_lt_i32_e64 s[2:3], s0, v177
	v_cvt_f32_i32_e32 v179, v105
	s_and_b64 vcc, vcc, s[2:3]
	s_nop 1
	v_cndmask_b32_e32 v142, v185, v179, vcc
	v_add_u32_e32 v105, -1, v104
	v_add_u32_e32 v177, 1, v140
	v_cmp_gt_u32_e32 vcc, 0x80, v105
	v_cmp_lt_i32_e64 s[2:3], s0, v177
	v_cvt_f32_i32_e32 v179, v105
	s_and_b64 vcc, vcc, s[2:3]
	s_nop 1
	v_cndmask_b32_e32 v141, v185, v179, vcc
	v_cmp_gt_u32_e32 vcc, 0x80, v104
	v_cmp_lt_i32_e64 s[2:3], s0, v140
	v_cvt_f32_i32_e32 v179, v104
	s_and_b64 vcc, vcc, s[2:3]
	s_nop 1
	v_cndmask_b32_e32 v140, v185, v179, vcc
	s_mov_b32 s36, 0x3e000000
	s_mov_b32 s37, 0x3e000000
	s_mov_b32 s40, 0x3fb8aa3b
	s_mov_b32 s41, 0x3fb8aa3b
	s_waitcnt lgkmcnt(0)
	s_barrier
	s_waitcnt vmcnt(0)

; DEV void attn_prompt_group(const Params& p, int l, int item, unsigned char* smem) {
;     ...
;     mx = fmaxf(mx, __shfl_xor(mx, 16)); mx = fmaxf(mx, __shfl_xor(mx, 32));
;     float sum = 0.f;
; #pragma unroll
;     for (int t = 0; t < 9; ++t)
; #pragma unroll
;       for (int j = 0; j < 4; ++j) { const float e = __expf(s[t][j] - mx); s[t][j] = e; sum += e; }
;     sum += __shfl_xor(sum, 16); sum += __shfl_xor(sum, 32);
.Lattn_nos:
	v_pk_mul_f32 v[186:187], v[108:109], s[38:39]
	v_pk_mul_f32 v[188:189], v[110:111], s[38:39]
	v_pk_mul_f32 v[190:191], v[112:113], s[38:39]
	v_pk_mul_f32 v[192:193], v[114:115], s[38:39]
	v_fma_f32 v161, v164, v178, v186
	v_fma_f32 v162, v165, v178, v187
	v_fma_f32 v163, v166, v178, v188
	v_fma_f32 v164, v167, v178, v189
	v_fma_f32 v165, v180, v178, v190
	v_fma_f32 v166, v181, v178, v191
	v_fma_f32 v167, v182, v178, v192
	v_fma_f32 v168, v183, v178, v193
	v_pk_mul_f32 v[186:187], v[116:117], s[38:39]
	v_pk_mul_f32 v[188:189], v[118:119], s[38:39]
	v_pk_fma_f32 v[96:97], v[96:97], s[36:37], v[186:187]
	v_pk_fma_f32 v[98:99], v[98:99], s[36:37], v[188:189]
	v_pk_mul_f32 v[190:191], v[120:121], s[38:39]
	v_pk_mul_f32 v[192:193], v[122:123], s[38:39]
	v_pk_fma_f32 v[92:93], v[92:93], s[36:37], v[190:191]
	v_pk_fma_f32 v[94:95], v[94:95], s[36:37], v[192:193]
	v_pk_mul_f32 v[186:187], v[124:125], s[38:39]
	v_pk_mul_f32 v[188:189], v[126:127], s[38:39]
	v_pk_fma_f32 v[88:89], v[88:89], s[36:37], v[186:187]
	v_pk_fma_f32 v[90:91], v[90:91], s[36:37], v[188:189]
	v_pk_mul_f32 v[190:191], v[128:129], s[38:39]
	v_pk_mul_f32 v[192:193], v[130:131], s[38:39]
	v_pk_fma_f32 v[84:85], v[84:85], s[36:37], v[190:191]
	v_pk_fma_f32 v[86:87], v[86:87], s[36:37], v[192:193]
	v_pk_mul_f32 v[186:187], v[132:133], s[38:39]
	v_pk_mul_f32 v[188:189], v[134:135], s[38:39]
	v_pk_fma_f32 v[80:81], v[80:81], s[36:37], v[186:187]
	v_pk_fma_f32 v[82:83], v[82:83], s[36:37], v[188:189]
	v_pk_mul_f32 v[190:191], v[136:137], s[38:39]
	v_pk_mul_f32 v[192:193], v[138:139], s[38:39]
	v_pk_fma_f32 v[76:77], v[76:77], s[36:37], v[190:191]
	v_pk_fma_f32 v[78:79], v[78:79], s[36:37], v[192:193]
	v_pk_mul_f32 v[186:187], v[140:141], s[38:39]
	v_pk_mul_f32 v[188:189], v[142:143], s[38:39]
	v_pk_fma_f32 v[72:73], v[72:73], s[36:37], v[186:187]
	v_pk_fma_f32 v[74:75], v[74:75], s[36:37], v[188:189]
	v_max3_f32 v186, v160, v161, v162
	v_max3_f32 v187, v163, v164, v165
	v_max3_f32 v186, v186, v166, v167
	v_max3_f32 v187, v187, v168, v96
	v_max3_f32 v186, v186, v97, v98
	v_max3_f32 v187, v187, v99, v92
	v_max3_f32 v186, v186, v93, v94
	v_max3_f32 v187, v187, v95, v88
	v_max3_f32 v186, v186, v89, v90
	v_max3_f32 v187, v187, v91, v84
	v_max3_f32 v186, v186, v85, v86
	v_max3_f32 v187, v187, v87, v80
	v_max3_f32 v186, v186, v81, v82
	v_max3_f32 v187, v187, v83, v76
	v_max3_f32 v186, v186, v77, v78
	v_max3_f32 v187, v187, v79, v72
	v_and_b32_e32 v177, 64, v202
	v_max3_f32 v186, v186, v73, v74
	v_max3_f32 v104, v186, v187, v75
	s_nop 0
	v_mov_b32_e32 v180, v104
	v_mov_b32_e32 v181, v104
	s_nop 1
	v_permlane16_swap_b32_e32 v180, v181
	s_nop 0
	v_max_f32_e32 v104, v180, v181
	s_nop 0
	v_mov_b32_e32 v180, v104
	v_mov_b32_e32 v181, v104
	s_nop 1
	v_permlane32_swap_b32_e32 v180, v181
	s_nop 0
	v_max_f32_e32 v104, v180, v181
	v_sub_f32_e32 v161, v161, v104
	v_sub_f32_e32 v168, v168, v104
	v_pk_add_f32 v[162:163], v[162:163], v[104:105] op_sel_hi:[1,0] neg_lo:[0,1] neg_hi:[0,1]
	v_pk_add_f32 v[164:165], v[164:165], v[104:105] op_sel_hi:[1,0] neg_lo:[0,1] neg_hi:[0,1]
	v_pk_add_f32 v[166:167], v[166:167], v[104:105] op_sel_hi:[1,0] neg_lo:[0,1] neg_hi:[0,1]
	v_mul_f32_e32 v161, 0x3fb8aa3b, v161
	v_mul_f32_e32 v168, 0x3fb8aa3b, v168
	v_pk_mul_f32 v[162:163], v[162:163], s[40:41]
	v_pk_mul_f32 v[164:165], v[164:165], s[40:41]
	v_pk_mul_f32 v[166:167], v[166:167], s[40:41]
	v_pk_add_f32 v[96:97], v[96:97], v[104:105] op_sel_hi:[1,0] neg_lo:[0,1] neg_hi:[0,1]
	v_pk_add_f32 v[98:99], v[98:99], v[104:105] op_sel_hi:[1,0] neg_lo:[0,1] neg_hi:[0,1]
	v_pk_mul_f32 v[96:97], v[96:97], s[40:41]
	v_pk_mul_f32 v[98:99], v[98:99], s[40:41]
	v_exp_f32_e32 v161, v161
	v_exp_f32_e32 v162, v162
	v_exp_f32_e32 v163, v163
	v_exp_f32_e32 v164, v164
	v_exp_f32_e32 v165, v165
	v_exp_f32_e32 v166, v166
	v_exp_f32_e32 v167, v167
	v_exp_f32_e32 v168, v168
	v_pk_add_f32 v[92:93], v[92:93], v[104:105] op_sel_hi:[1,0] neg_lo:[0,1] neg_hi:[0,1]
	v_pk_add_f32 v[94:95], v[94:95], v[104:105] op_sel_hi:[1,0] neg_lo:[0,1] neg_hi:[0,1]
	v_pk_mul_f32 v[92:93], v[92:93], s[40:41]
	v_pk_mul_f32 v[94:95], v[94:95], s[40:41]
	v_add_f32_e32 v179, 0, v161
	v_add_f32_e32 v179, v162, v179
	v_add_f32_e32 v179, v163, v179
	v_add_f32_e32 v179, v164, v179
	v_add_f32_e32 v179, v165, v179
	v_add_f32_e32 v179, v166, v179
	v_add_f32_e32 v179, v167, v179
	v_add_f32_e32 v179, v168, v179
	v_exp_f32_e32 v96, v96
	v_exp_f32_e32 v97, v97
	v_exp_f32_e32 v98, v98
	v_exp_f32_e32 v99, v99
	v_pk_add_f32 v[88:89], v[88:89], v[104:105] op_sel_hi:[1,0] neg_lo:[0,1] neg_hi:[0,1]
	v_pk_add_f32 v[90:91], v[90:91], v[104:105] op_sel_hi:[1,0] neg_lo:[0,1] neg_hi:[0,1]
	v_pk_mul_f32 v[88:89], v[88:89], s[40:41]
	v_pk_mul_f32 v[90:91], v[90:91], s[40:41]
	v_add_f32_e32 v179, v96, v179
	v_add_f32_e32 v179, v97, v179
	v_add_f32_e32 v179, v98, v179
	v_add_f32_e32 v179, v99, v179
	v_exp_f32_e32 v92, v92
	v_exp_f32_e32 v93, v93
	v_exp_f32_e32 v94, v94
	v_exp_f32_e32 v95, v95
	v_pk_add_f32 v[84:85], v[84:85], v[104:105] op_sel_hi:[1,0] neg_lo:[0,1] neg_hi:[0,1]
	v_pk_add_f32 v[86:87], v[86:87], v[104:105] op_sel_hi:[1,0] neg_lo:[0,1] neg_hi:[0,1]
	v_pk_mul_f32 v[84:85], v[84:85], s[40:41]
	v_pk_mul_f32 v[86:87], v[86:87], s[40:41]
	v_add_f32_e32 v179, v92, v179
	v_add_f32_e32 v179, v93, v179
	v_add_f32_e32 v179, v94, v179
	v_add_f32_e32 v179, v95, v179
	v_exp_f32_e32 v181, v88
	v_exp_f32_e32 v180, v89
	v_exp_f32_e32 v182, v90
	v_exp_f32_e32 v183, v91
	v_pk_add_f32 v[80:81], v[80:81], v[104:105] op_sel_hi:[1,0] neg_lo:[0,1] neg_hi:[0,1]
	v_pk_add_f32 v[82:83], v[82:83], v[104:105] op_sel_hi:[1,0] neg_lo:[0,1] neg_hi:[0,1]
	v_pk_mul_f32 v[80:81], v[80:81], s[40:41]
; DEV f32x4 mfma16(bf16x4 a, bf16x4 b, f32x4 c) { return __builtin_amdgcn_mfma_f32_16x16x16bf16_1k(a, b, c, 0, 0, 0); }
; DEV void attn_prompt_group(const Params& p, int l, int item, unsigned char* smem) {
;     ...
;     for (int t = 0; t < 9; ++t)
; #pragma unroll
;       for (int j = 0; j < 4; ++j) { const float e = __expf(s[t][j] - mx); s[t][j] = e; sum += e; }
;     sum += __shfl_xor(sum, 16); sum += __shfl_xor(sum, 32);
;     const float denom = sum + __expf(sink - mx);
;     f32x4 o[4];
; #pragma unroll
;     for (int dt = 0; dt < 4; ++dt) o[dt] = (f32x4){0.f, 0.f, 0.f, 0.f};
; #pragma unroll
;     for (int t = 0; t < 9; ++t) {
;       const bf16x4 pf = pack4(s[t][0], s[t][1], s[t][2], s[t][3]);
; #pragma unroll
;       for (int dt = 0; dt < 4; ++dt) {
;         const bf16x4 vf = *(const bf16x4*)(Vt + (dt * 16 + fr) * 264 + (w + t) * 16 + fq * 4);
;         o[dt] = mfma16(pf, vf, o[dt]);
;       }
;     }
	v_pk_mul_f32 v[82:83], v[82:83], s[40:41]
	v_add_f32_e32 v179, v181, v179
	v_add_f32_e32 v179, v180, v179
	v_add_f32_e32 v179, v182, v179
	v_add_f32_e32 v179, v183, v179
	v_exp_f32_e32 v184, v84
	v_exp_f32_e32 v185, v85
	v_exp_f32_e32 v186, v86
	v_exp_f32_e32 v187, v87
	v_pk_add_f32 v[76:77], v[76:77], v[104:105] op_sel_hi:[1,0] neg_lo:[0,1] neg_hi:[0,1]
	v_pk_add_f32 v[78:79], v[78:79], v[104:105] op_sel_hi:[1,0] neg_lo:[0,1] neg_hi:[0,1]
	v_pk_mul_f32 v[76:77], v[76:77], s[40:41]
	v_pk_mul_f32 v[78:79], v[78:79], s[40:41]
	v_add_f32_e32 v179, v184, v179
	v_add_f32_e32 v179, v185, v179
	v_add_f32_e32 v179, v186, v179
	v_add_f32_e32 v179, v187, v179
	v_exp_f32_e32 v188, v80
	v_exp_f32_e32 v189, v81
	v_exp_f32_e32 v190, v82
	v_exp_f32_e32 v191, v83
	v_pk_add_f32 v[72:73], v[72:73], v[104:105] op_sel_hi:[1,0] neg_lo:[0,1] neg_hi:[0,1]
	v_pk_add_f32 v[74:75], v[74:75], v[104:105] op_sel_hi:[1,0] neg_lo:[0,1] neg_hi:[0,1]
	v_pk_mul_f32 v[72:73], v[72:73], s[40:41]
	v_pk_mul_f32 v[74:75], v[74:75], s[40:41]
	v_add_f32_e32 v179, v188, v179
	v_add_f32_e32 v179, v189, v179
	v_add_f32_e32 v179, v190, v179
	v_add_f32_e32 v179, v191, v179
	v_exp_f32_e32 v192, v76
	v_exp_f32_e32 v193, v77
	v_exp_f32_e32 v194, v78
	v_exp_f32_e32 v195, v79
	s_nop 0
	v_add_f32_e32 v179, v192, v179
	v_add_f32_e32 v179, v193, v179
	v_add_f32_e32 v179, v194, v179
	v_add_f32_e32 v179, v195, v179
	v_exp_f32_e32 v196, v72
	v_exp_f32_e32 v197, v73
	v_exp_f32_e32 v198, v74
	v_exp_f32_e32 v199, v75
	s_nop 0
	v_add_f32_e32 v179, v196, v179
	v_add_f32_e32 v179, v197, v179
	v_add_f32_e32 v179, v198, v179
	v_add_f32_e32 v72, v199, v179
	v_mov_b32_e32 v73, v72
	v_cvt_pk_bf16_f32 v84, v161, v162
	v_cvt_pk_bf16_f32 v85, v163, v164
	v_permlane16_swap_b32_e32 v72, v73
	v_sub_f32_e32 v74, v160, v104
	v_mul_f32_e32 v74, 0x3fb8aa3b, v74
	v_add_f32_e32 v72, v72, v73
	v_cvt_pk_bf16_f32 v88, v165, v166
	v_cvt_pk_bf16_f32 v89, v167, v168
	v_mov_b32_e32 v73, v72
	ds_read_b64 v[90:91], v148
	v_exp_f32_e32 v104, v74
	s_nop 1
	v_permlane32_swap_b32_e32 v72, v73
	s_nop 0
	v_add_f32_e32 v105, v72, v73
	ds_read_b64 v[72:73], v147
	ds_read_b64 v[76:77], v147 offset:8448
	ds_read_b64 v[80:81], v147 offset:16896
	ds_read_b64 v[86:87], v147 offset:25344
	s_waitcnt lgkmcnt(3)
	v_mfma_f32_16x16x16_bf16 v[72:75], v[84:85], v[72:73], 0
	v_mfma_f32_16x16x16_bf16 v[72:75], v[88:89], v[90:91], v[72:75]
	ds_read_b64 v[90:91], v148 offset:8448
	s_waitcnt lgkmcnt(3)
	v_mfma_f32_16x16x16_bf16 v[76:79], v[84:85], v[76:77], 0
	s_waitcnt lgkmcnt(0)
	v_mfma_f32_16x16x16_bf16 v[76:79], v[88:89], v[90:91], v[76:79]
	ds_read_b64 v[90:91], v148 offset:16896
	v_mfma_f32_16x16x16_bf16 v[80:83], v[84:85], v[80:81], 0
	s_waitcnt lgkmcnt(0)
	v_mfma_f32_16x16x16_bf16 v[80:83], v[88:89], v[90:91], v[80:83]
	ds_read_b64 v[90:91], v148 offset:25344
	v_mfma_f32_16x16x16_bf16 v[84:87], v[84:85], v[86:87], 0
	s_waitcnt lgkmcnt(0)
	v_mfma_f32_16x16x16_bf16 v[84:87], v[88:89], v[90:91], v[84:87]
	ds_read_b64 v[218:219], v149
	ds_read_b64 v[220:221], v149 offset:8448
	ds_read_b64 v[222:223], v149 offset:16896
	ds_read_b64 v[224:225], v149 offset:25344
	v_cvt_pk_bf16_f32 v88, v96, v97
	v_cvt_pk_bf16_f32 v89, v98, v99
	ds_read_b64 v[226:227], v150
	ds_read_b64 v[228:229], v150 offset:8448
	ds_read_b64 v[230:231], v150 offset:16896
	ds_read_b64 v[232:233], v150 offset:25344
	s_waitcnt lgkmcnt(4)
	v_mfma_f32_16x16x16_bf16 v[72:75], v[88:89], v[218:219], v[72:75]
	v_mfma_f32_16x16x16_bf16 v[76:79], v[88:89], v[220:221], v[76:79]
	v_mfma_f32_16x16x16_bf16 v[80:83], v[88:89], v[222:223], v[80:83]
	v_mfma_f32_16x16x16_bf16 v[84:87], v[88:89], v[224:225], v[84:87]
	v_cvt_pk_bf16_f32 v88, v92, v93
	v_cvt_pk_bf16_f32 v89, v94, v95
	ds_read_b64 v[218:219], v151
	ds_read_b64 v[220:221], v151 offset:8448
	ds_read_b64 v[222:223], v151 offset:16896
	ds_read_b64 v[224:225], v151 offset:25344
	s_waitcnt lgkmcnt(4)
	v_mfma_f32_16x16x16_bf16 v[72:75], v[88:89], v[226:227], v[72:75]
	v_mfma_f32_16x16x16_bf16 v[76:79], v[88:89], v[228:229], v[76:79]
	v_mfma_f32_16x16x16_bf16 v[80:83], v[88:89], v[230:231], v[80:83]
	v_mfma_f32_16x16x16_bf16 v[84:87], v[88:89], v[232:233], v[84:87]
	v_cvt_pk_bf16_f32 v88, v181, v180
	v_cvt_pk_bf16_f32 v89, v182, v183
	ds_read_b64 v[226:227], v152
	ds_read_b64 v[228:229], v152 offset:8448
	ds_read_b64 v[230:231], v152 offset:16896
	ds_read_b64 v[232:233], v152 offset:25344
	s_waitcnt lgkmcnt(4)
	v_mfma_f32_16x16x16_bf16 v[72:75], v[88:89], v[218:219], v[72:75]
	v_mfma_f32_16x16x16_bf16 v[76:79], v[88:89], v[220:221], v[76:79]
	v_mfma_f32_16x16x16_bf16 v[80:83], v[88:89], v[222:223], v[80:83]
	v_mfma_f32_16x16x16_bf16 v[84:87], v[88:89], v[224:225], v[84:87]
	v_cvt_pk_bf16_f32 v88, v184, v185
	v_cvt_pk_bf16_f32 v89, v186, v187
	ds_read_b64 v[218:219], v153
	ds_read_b64 v[220:221], v153 offset:8448
	ds_read_b64 v[222:223], v153 offset:16896
	ds_read_b64 v[224:225], v153 offset:25344
	s_waitcnt lgkmcnt(4)
; DEV bf16_t f2bf(float f) { return (bf16_t)(cvt_pk_bf16(f, 0.f) & 0xffffu); }
; DEV f32x4 mfma16(bf16x4 a, bf16x4 b, f32x4 c) { return __builtin_amdgcn_mfma_f32_16x16x16bf16_1k(a, b, c, 0, 0, 0); }
; DEV void attn_prompt_group(const Params& p, int l, int item, unsigned char* smem) {
;     ...
;     for (int t = 0; t < 9; ++t) {
;       const bf16x4 pf = pack4(s[t][0], s[t][1], s[t][2], s[t][3]);
; #pragma unroll
;       for (int dt = 0; dt < 4; ++dt) {
;         const bf16x4 vf = *(const bf16x4*)(Vt + (dt * 16 + fr) * 264 + (w + t) * 16 + fq * 4);
;         o[dt] = mfma16(pf, vf, o[dt]);
;       }
;     }
;     bf16_t* Os = (bf16_t*)(smem + 33792 + w * 2304);
; #pragma unroll
;     for (int j = 0; j < 4; ++j) {
;       const int r = fq * 4 + j;
;       const float inv = 1.0f / __shfl(denom, r);
; #pragma unroll
;       for (int dt = 0; dt < 4; ++dt) Os[r * 72 + dt * 16 + fr] = f2bf(o[dt][j] * inv);
;     }
;     asm volatile("s_waitcnt lgkmcnt(0)" ::: "memory");
; #pragma unroll
;     for (int i = 0; i < 2; ++i) {
;       const int c = lane + i * 64, r = c >> 3, kc = c & 7;
;       const u32x4 v = *(const u32x4*)(Os + r * 72 + kc * 8);
;       *(u32x4*)(Z + (rowbase + w * 16 + r) * NIN + AQ + h * 64 + kc * 8) = v;
;     }
;     asm volatile("s_waitcnt lgkmcnt(0)" ::: "memory");
;   }
	v_mfma_f32_16x16x16_bf16 v[72:75], v[88:89], v[226:227], v[72:75]
	v_mfma_f32_16x16x16_bf16 v[76:79], v[88:89], v[228:229], v[76:79]
	v_mfma_f32_16x16x16_bf16 v[80:83], v[88:89], v[230:231], v[80:83]
	v_mfma_f32_16x16x16_bf16 v[84:87], v[88:89], v[232:233], v[84:87]
	v_cvt_pk_bf16_f32 v88, v188, v189
	v_cvt_pk_bf16_f32 v89, v190, v191
	ds_read_b64 v[226:227], v154
	ds_read_b64 v[228:229], v154 offset:8448
	ds_read_b64 v[230:231], v154 offset:16896
	ds_read_b64 v[232:233], v154 offset:25344
	s_waitcnt lgkmcnt(4)
	v_mfma_f32_16x16x16_bf16 v[72:75], v[88:89], v[218:219], v[72:75]
	v_mfma_f32_16x16x16_bf16 v[76:79], v[88:89], v[220:221], v[76:79]
	v_mfma_f32_16x16x16_bf16 v[80:83], v[88:89], v[222:223], v[80:83]
	v_mfma_f32_16x16x16_bf16 v[84:87], v[88:89], v[224:225], v[84:87]
	v_cvt_pk_bf16_f32 v88, v192, v193
	v_cvt_pk_bf16_f32 v89, v194, v195
	ds_read_b64 v[218:219], v155
	ds_read_b64 v[220:221], v155 offset:8448
	ds_read_b64 v[222:223], v155 offset:16896
	ds_read_b64 v[224:225], v155 offset:25344
	s_waitcnt lgkmcnt(4)
	v_mfma_f32_16x16x16_bf16 v[72:75], v[88:89], v[226:227], v[72:75]
	v_mfma_f32_16x16x16_bf16 v[76:79], v[88:89], v[228:229], v[76:79]
	v_mfma_f32_16x16x16_bf16 v[80:83], v[88:89], v[230:231], v[80:83]
	v_mfma_f32_16x16x16_bf16 v[84:87], v[88:89], v[232:233], v[84:87]
	v_cvt_pk_bf16_f32 v88, v196, v197
	v_cvt_pk_bf16_f32 v89, v198, v199
	s_nop 0
	s_waitcnt lgkmcnt(0)
	v_mfma_f32_16x16x16_bf16 v[72:75], v[88:89], v[218:219], v[72:75]
	v_mfma_f32_16x16x16_bf16 v[76:79], v[88:89], v[220:221], v[76:79]
	v_mfma_f32_16x16x16_bf16 v[80:83], v[88:89], v[222:223], v[80:83]
	v_mfma_f32_16x16x16_bf16 v[84:87], v[88:89], v[224:225], v[84:87]
	v_add_f32_e32 v88, v104, v105
	v_or_b32_e32 v89, v177, v107
	v_div_scale_f32 v90, s[0:1], v88, v88, 1.0
	v_or_b32_e32 v95, v177, v144
	v_rcp_f32_e32 v91, v90
	v_lshlrev_b32_e32 v89, 2, v89
	v_fma_f32 v92, -v90, v91, 1.0
	v_fmac_f32_e32 v91, v92, v91
	v_div_scale_f32 v92, vcc, 1.0, v88, 1.0
	v_mul_f32_e32 v93, v92, v91
	v_fma_f32 v94, -v90, v93, v92
	v_fmac_f32_e32 v93, v94, v91
	v_fma_f32 v90, -v90, v93, v92
	v_div_fmas_f32 v90, v90, v91, v93
	v_div_fixup_f32 v88, v90, v88, 1.0
	v_or_b32_e32 v90, v177, v145
	v_or_b32_e32 v91, v177, v146
	v_lshlrev_b32_e32 v95, 2, v95
	v_lshlrev_b32_e32 v90, 2, v90
	v_lshlrev_b32_e32 v91, 2, v91
	ds_bpermute_b32 v89, v89, v88
	ds_bpermute_b32 v95, v95, v88
	ds_bpermute_b32 v90, v90, v88
	ds_bpermute_b32 v91, v91, v88
	s_waitcnt lgkmcnt(3)
	v_mul_f32_e32 v72, v72, v89
	v_mul_f32_e32 v76, v76, v89
	v_mul_f32_e32 v80, v80, v89
	v_mul_f32_e32 v84, v84, v89
	s_waitcnt lgkmcnt(2)
	v_mul_f32_e32 v73, v73, v95
	v_mul_f32_e32 v77, v77, v95
	v_mul_f32_e32 v81, v81, v95
	v_mul_f32_e32 v85, v85, v95
	s_waitcnt lgkmcnt(1)
	v_mul_f32_e32 v74, v74, v90
	v_mul_f32_e32 v78, v78, v90
	v_mul_f32_e32 v82, v82, v90
	v_mul_f32_e32 v86, v86, v90
	s_waitcnt lgkmcnt(0)
	v_mul_f32_e32 v75, v75, v91
	v_mul_f32_e32 v79, v79, v91
	v_mul_f32_e32 v83, v83, v91
	v_mul_f32_e32 v87, v87, v91
	v_cvt_pk_bf16_f32 v72, v72, v76
	v_cvt_pk_bf16_f32 v80, v80, v84
	ds_write_b16 v156, v72 offset:33792
	ds_write_b16_d16_hi v156, v72 offset:33824
	ds_write_b16 v156, v80 offset:33856
	ds_write_b16_d16_hi v156, v80 offset:33888
	v_cvt_pk_bf16_f32 v73, v73, v77
	v_cvt_pk_bf16_f32 v81, v81, v85
	ds_write_b16 v157, v73 offset:33792
	ds_write_b16_d16_hi v157, v73 offset:33824
	ds_write_b16 v157, v81 offset:33856
	ds_write_b16_d16_hi v157, v81 offset:33888
	v_cvt_pk_bf16_f32 v74, v74, v78
	v_cvt_pk_bf16_f32 v82, v82, v86
	ds_write_b16 v157, v74 offset:33936
	ds_write_b16_d16_hi v157, v74 offset:33968
	ds_write_b16 v157, v82 offset:34000
	ds_write_b16_d16_hi v157, v82 offset:34032
	v_cvt_pk_bf16_f32 v75, v75, v79
	v_cvt_pk_bf16_f32 v83, v83, v87
	ds_write_b16 v157, v75 offset:34080
	ds_write_b16_d16_hi v157, v75 offset:34112
	ds_write_b16 v157, v83 offset:34144
	ds_write_b16_d16_hi v157, v83 offset:34176
	s_waitcnt lgkmcnt(0)
	ds_read_b128 v[72:75], v158 offset:33792
	v_lshl_add_u64 v[76:77], v[100:101], 0, s[90:91]
	s_mov_b32 s0, 0x4700000
	v_add_co_u32_e32 v78, vcc, s0, v76
	s_mov_b32 s0, 0x471b000
	s_nop 0
	v_addc_co_u32_e32 v79, vcc, 0, v77, vcc
	s_waitcnt lgkmcnt(0)
	global_store_dwordx4 v[78:79], v[72:75], off offset:3072
	ds_read_b128 v[72:75], v159 offset:33792
	v_add_co_u32_e32 v76, vcc, s0, v76
	s_add_u32 s90, s90, 0x80
	s_nop 0
	v_addc_co_u32_e32 v77, vcc, 0, v77, vcc
	s_waitcnt lgkmcnt(0)
	global_store_dwordx4 v[76:77], v[72:75], off offset:3072
	s_addc_u32 s91, s91, 0
	s_waitcnt lgkmcnt(0)
	s_add_u32 s18, s18, 4
	s_addc_u32 s19, s19, 0
	s_add_i32 s6, s6, 1
	s_waitcnt vmcnt(2)
	s_cmpk_lg_i32 s90, 0x200
	s_cbranch_scc1 .LBB0_477
	v_readlane_b32 s76, v248, 47
	v_readlane_b32 s77, v248, 48
	v_readlane_b32 s78, v248, 49
	v_readlane_b32 s79, v248, 50
	v_readlane_b32 s80, v248, 51
	v_readlane_b32 s81, v248, 52
	v_readlane_b32 s82, v248, 53
	v_readlane_b32 s83, v248, 54
	v_readlane_b32 s84, v248, 55
	v_readlane_b32 s85, v248, 56
	v_readlane_b32 s86, v248, 57
	v_readlane_b32 s87, v248, 58
	v_readlane_b32 s88, v248, 59
	v_readlane_b32 s89, v248, 60
	v_readlane_b32 s90, v248, 61
	v_readlane_b32 s91, v248, 62
	s_movk_i32 s75, 0x900
	s_barrier
	s_branch .LBB0_428
